# gate|up miss path and row epilogues: xor-16/xor-32 ds_bpermute+add reductions replaced by v_permlane16_swap/v_permlane32_swap where the consumer is a plain add (58 sites)
# speedup vs baseline: 1.0073x; 1.0001x over previous
.Lepc_miss:
	v_lshl_add_u32 v180, s34, 8, v184
	v_ashrrev_i32_e32 v181, 31, v180
	v_lshlrev_b64 v[128:129], 6, v[180:181]
	v_or_b32_e32 v178, 16, v180
	v_lshl_add_u64 v[128:129], v[158:159], 0, v[128:129]
	v_ashrrev_i32_e32 v179, 31, v178
	global_load_dwordx4 v[188:191], v[128:129], off
	v_lshlrev_b64 v[128:129], 6, v[178:179]
	v_lshl_add_u64 v[128:129], v[158:159], 0, v[128:129]
	global_load_dwordx4 v[192:195], v[128:129], off
	v_or_b32_e32 v176, 32, v180
	v_ashrrev_i32_e32 v177, 31, v176
	v_lshlrev_b64 v[128:129], 6, v[176:177]
	v_or_b32_e32 v174, 48, v180
	v_lshl_add_u64 v[128:129], v[158:159], 0, v[128:129]
	v_ashrrev_i32_e32 v175, 31, v174
	global_load_dwordx4 v[148:151], v[128:129], off
	v_lshlrev_b64 v[128:129], 6, v[174:175]
	v_lshl_add_u64 v[128:129], v[158:159], 0, v[128:129]
	global_load_dwordx4 v[144:147], v[128:129], off
	v_add_u32_e32 v172, 0x80, v180
	v_ashrrev_i32_e32 v173, 31, v172
	v_lshlrev_b64 v[128:129], 6, v[172:173]
	v_add_u32_e32 v170, 0x90, v180
	v_lshl_add_u64 v[128:129], v[158:159], 0, v[128:129]
	v_ashrrev_i32_e32 v171, 31, v170
	global_load_dwordx4 v[140:143], v[128:129], off
	v_lshlrev_b64 v[128:129], 6, v[170:171]
	v_lshl_add_u64 v[128:129], v[158:159], 0, v[128:129]
	global_load_dwordx4 v[136:139], v[128:129], off
	v_add_u32_e32 v168, 0xa0, v180
	v_ashrrev_i32_e32 v169, 31, v168
	v_lshlrev_b64 v[128:129], 6, v[168:169]
	v_add_u32_e32 v166, 0xb0, v180
	v_lshl_add_u64 v[128:129], v[158:159], 0, v[128:129]
	v_ashrrev_i32_e32 v167, 31, v166
	global_load_dwordx4 v[132:135], v[128:129], off
	v_lshlrev_b64 v[128:129], 6, v[166:167]
	v_lshl_add_u64 v[128:129], v[158:159], 0, v[128:129]
	global_load_dwordx4 v[128:131], v[128:129], off
	v_and_b32_e32 v169, 64, v222
	v_xor_b32_e32 v167, 16, v222
	v_add_u32_e32 v169, 64, v169
	v_cmp_lt_i32_e32 vcc, v167, v169
	s_mov_b32 s34, 0x358637bd
	v_readlane_b32 s40, v249, 54
	v_cndmask_b32_e32 v167, v222, v167, vcc
	v_lshlrev_b32_e32 v173, 2, v167
	v_xor_b32_e32 v167, 32, v222
	v_cmp_lt_i32_e32 vcc, v167, v169
	v_readlane_b32 s41, v249, 55
	v_readlane_b32 s50, v250, 58
	v_cndmask_b32_e32 v167, v222, v167, vcc
	v_lshlrev_b32_e32 v171, 2, v167
	v_pk_mul_f32 v[124:125], v[120:121], v[124:125]
	v_pk_mul_f32 v[116:117], v[112:113], v[116:117]
	v_pk_mul_f32 v[108:109], v[104:105], v[108:109]
	v_pk_mul_f32 v[100:101], v[96:97], v[100:101]
	v_pk_mul_f32 v[92:93], v[88:89], v[92:93]
	v_pk_mul_f32 v[84:85], v[80:81], v[84:85]
	v_pk_mul_f32 v[76:77], v[72:73], v[76:77]
	v_pk_mul_f32 v[68:69], v[64:65], v[68:69]
	v_pk_mul_f32 v[60:61], v[56:57], v[60:61]
	v_pk_mul_f32 v[52:53], v[48:49], v[52:53]
	v_pk_mul_f32 v[44:45], v[40:41], v[44:45]
	v_pk_mul_f32 v[36:37], v[32:33], v[36:37]
	v_pk_mul_f32 v[28:29], v[24:25], v[28:29]
	v_pk_mul_f32 v[20:21], v[16:17], v[20:21]
	v_pk_mul_f32 v[12:13], v[8:9], v[12:13]
	v_pk_mul_f32 v[4:5], v[0:1], v[4:5]
	v_readlane_b32 s51, v250, 59
	s_waitcnt vmcnt(0)
	v_mov_b32_e32 v182, v189
	v_mov_b32_e32 v183, v190
	v_mov_b32_e32 v189, v191
	v_pk_add_f32 v[182:183], v[182:183], v[188:189]
	v_mov_b32_e32 v188, v193
	v_mov_b32_e32 v189, v194
	v_mov_b32_e32 v193, v195
	v_pk_add_f32 v[188:189], v[188:189], v[192:193]
	v_mov_b32_e32 v191, v182
	v_mov_b32_e32 v190, v188
	v_mov_b32_e32 v182, v189
	v_pk_add_f32 v[182:183], v[190:191], v[182:183]
	v_mov_b32_e32 v189, v183
	s_nop 1
	v_permlane16_swap_b32_e32 v183, v189
	v_mov_b32_e32 v188, v182
	s_nop 1
	v_permlane16_swap_b32_e32 v182, v188
	s_waitcnt lgkmcnt(0)
	v_pk_add_f32 v[182:183], v[182:183], v[188:189]
	v_mov_b32_e32 v189, v183
	s_nop 1
	v_permlane32_swap_b32_e32 v183, v189
	v_mov_b32_e32 v188, v182
	s_nop 1
	v_permlane32_swap_b32_e32 v182, v188
	s_waitcnt lgkmcnt(0)
	v_pk_add_f32 v[188:189], v[182:183], v[188:189]
	v_mov_b64_e32 v[182:183], s[34:35]
	s_mov_b32 s34, 0x3a800000
	v_pk_fma_f32 v[188:189], v[188:189], s[34:35], v[182:183] op_sel_hi:[1,0,0]
	s_nop 0
	v_mul_f32_e32 v167, 0x4b800000, v189
	v_cmp_gt_f32_e64 s[44:45], s39, v189
	v_cmp_gt_f32_e32 vcc, s39, v188
	s_nop 0
	v_cndmask_b32_e64 v167, v189, v167, s[44:45]
	v_rsq_f32_e32 v167, v167
	v_mov_b32_e32 v189, v150
	v_mov_b32_e32 v150, v145
	v_mov_b32_e32 v145, v147
	v_mul_f32_e32 v169, 0x45800000, v167
	v_cndmask_b32_e64 v169, v167, v169, s[44:45]
	v_mul_f32_e32 v167, 0x4b800000, v188
	v_cndmask_b32_e32 v167, v188, v167, vcc
	v_mov_b32_e32 v188, v149
	v_mov_b32_e32 v149, v151
	v_mov_b32_e32 v151, v146
	v_pk_add_f32 v[148:149], v[188:189], v[148:149]
	v_pk_add_f32 v[144:145], v[150:151], v[144:145]
	v_mov_b32_e32 v147, v148
	v_mov_b32_e32 v146, v144
	v_mov_b32_e32 v148, v145
	v_pk_add_f32 v[144:145], v[146:147], v[148:149]
	v_mov_b32_e32 v147, v145
	s_nop 1
	v_permlane16_swap_b32_e32 v145, v147
	v_mov_b32_e32 v146, v144
	s_nop 1
	v_permlane16_swap_b32_e32 v144, v146
	v_mov_b32_e32 v148, v141
	v_mov_b32_e32 v149, v142
	v_mov_b32_e32 v141, v143
	v_mov_b32_e32 v142, v137
	v_mov_b32_e32 v143, v138
	v_mov_b32_e32 v137, v139
	v_pk_add_f32 v[140:141], v[148:149], v[140:141]
	v_pk_add_f32 v[136:137], v[142:143], v[136:137]
	s_waitcnt lgkmcnt(0)
	v_pk_add_f32 v[144:145], v[144:145], v[146:147]
	v_mov_b32_e32 v138, v136
	v_mov_b32_e32 v139, v140
	v_mov_b32_e32 v140, v137
	v_mov_b32_e32 v147, v145
	s_nop 1
	v_permlane32_swap_b32_e32 v145, v147
	v_mov_b32_e32 v146, v144
	s_nop 1
	v_permlane32_swap_b32_e32 v144, v146
	v_pk_add_f32 v[136:137], v[138:139], v[140:141]
	v_mov_b32_e32 v139, v137
	s_nop 1
	v_permlane16_swap_b32_e32 v137, v139
	v_mov_b32_e32 v138, v136
	s_nop 1
	v_permlane16_swap_b32_e32 v136, v138
	v_rsq_f32_e32 v167, v167
	s_waitcnt lgkmcnt(2)
	v_pk_add_f32 v[144:145], v[144:145], v[146:147]
	v_mul_f32_e32 v150, v169, v169
	v_pk_fma_f32 v[144:145], v[144:145], s[34:35], v[182:183] op_sel_hi:[1,0,0]
	s_waitcnt lgkmcnt(0)
	v_pk_add_f32 v[136:137], v[136:137], v[138:139]
	v_mul_f32_e32 v146, 0x4b800000, v145
	v_cmp_gt_f32_e64 s[44:45], s39, v145
	v_mov_b32_e32 v139, v137
	s_nop 1
	v_permlane32_swap_b32_e32 v137, v139
	v_mov_b32_e32 v138, v136
	s_nop 1
	v_permlane32_swap_b32_e32 v136, v138
	v_cndmask_b32_e64 v145, v145, v146, s[44:45]
	v_rsq_f32_e32 v145, v145
	v_mul_f32_e32 v175, 0x45800000, v167
	v_cndmask_b32_e32 v167, v167, v175, vcc
	s_waitcnt lgkmcnt(0)
	v_pk_add_f32 v[136:137], v[136:137], v[138:139]
	v_mul_f32_e32 v146, 0x45800000, v145
	v_pk_fma_f32 v[136:137], v[136:137], s[34:35], v[182:183] op_sel_hi:[1,0,0]
	v_cmp_gt_f32_e32 vcc, s39, v144
	v_cndmask_b32_e64 v147, v145, v146, s[44:45]
	v_mul_f32_e32 v145, 0x4b800000, v144
	v_mul_f32_e32 v138, 0x4b800000, v137
	v_cmp_gt_f32_e64 s[44:45], s39, v137
	v_cndmask_b32_e32 v144, v144, v145, vcc
	v_rsq_f32_e32 v144, v144
	v_cndmask_b32_e64 v137, v137, v138, s[44:45]
	v_rsq_f32_e32 v137, v137
	v_mul_f32_e32 v148, v167, v167
	v_mul_f32_e32 v145, 0x45800000, v144
	v_cndmask_b32_e32 v145, v144, v145, vcc
	v_mul_f32_e32 v138, 0x45800000, v137
	v_cmp_gt_f32_e32 vcc, s39, v136
	v_cndmask_b32_e64 v143, v137, v138, s[44:45]
	v_mul_f32_e32 v137, 0x4b800000, v136
	v_cndmask_b32_e32 v136, v136, v137, vcc
	v_rsq_f32_e32 v136, v136
	v_mul_f32_e32 v146, v147, v147
	v_mul_f32_e32 v144, v145, v145
	v_mul_f32_e32 v142, v143, v143
	v_mul_f32_e32 v137, 0x45800000, v136
	v_cndmask_b32_e32 v141, v136, v137, vcc
	v_mov_b32_e32 v136, v133
	v_mov_b32_e32 v137, v134
	v_mov_b32_e32 v133, v135
	v_mov_b32_e32 v134, v129
	v_mov_b32_e32 v135, v130
	v_mov_b32_e32 v129, v131
	v_pk_add_f32 v[132:133], v[136:137], v[132:133]
	v_pk_add_f32 v[128:129], v[134:135], v[128:129]
	v_mov_b32_e32 v131, v132
	v_mov_b32_e32 v130, v128
	v_mov_b32_e32 v132, v129
	v_pk_add_f32 v[128:129], v[130:131], v[132:133]
	v_mov_b32_e32 v131, v129
	s_nop 1
	v_permlane16_swap_b32_e32 v129, v131
	v_mov_b32_e32 v130, v128
	s_nop 1
	v_permlane16_swap_b32_e32 v128, v130
	v_lshl_or_b32 v132, s33, 7, v186
	v_ashrrev_i32_e32 v133, 31, v132
	v_lshlrev_b64 v[136:137], 1, v[132:133]
	v_mul_f32_e32 v140, v141, v141
	s_waitcnt lgkmcnt(0)
	v_pk_add_f32 v[128:129], v[128:129], v[130:131]
	v_mov_b32_e32 v131, v129
	s_nop 1
	v_permlane32_swap_b32_e32 v129, v131
	v_mov_b32_e32 v130, v128
	s_nop 1
	v_permlane32_swap_b32_e32 v128, v130
	s_waitcnt lgkmcnt(0)
	v_pk_add_f32 v[128:129], v[128:129], v[130:131]
	s_nop 0
	v_pk_fma_f32 v[128:129], v[128:129], s[34:35], v[182:183] op_sel_hi:[1,0,0]
	s_mov_b64 s[34:35], -1
	v_mul_f32_e32 v130, 0x4b800000, v129
	v_cmp_gt_f32_e64 s[44:45], s39, v129
	v_cmp_gt_f32_e32 vcc, s39, v128
	s_nop 0
	v_cndmask_b32_e64 v129, v129, v130, s[44:45]
	v_rsq_f32_e32 v129, v129
	s_nop 0
	v_mul_f32_e32 v130, 0x45800000, v129
	v_cndmask_b32_e64 v139, v129, v130, s[44:45]
	v_mul_f32_e32 v129, 0x4b800000, v128
	v_cndmask_b32_e32 v128, v128, v129, vcc
	v_rsq_f32_e32 v128, v128
	v_mul_f32_e32 v138, v139, v139
	v_mul_f32_e32 v129, 0x45800000, v128
	v_cndmask_b32_e32 v135, v128, v129, vcc
	v_lshrrev_b32_e32 v182, 6, v199
	v_and_b32_e32 v183, 15, v199
	v_lshlrev_b32_e32 v182, 9, v182
	v_lshl_add_u32 v183, v183, 2, v182
	v_add_u32_e32 v183, 0x20040, v183
	ds_write_b32 v183, v169
	ds_write_b32 v183, v167 offset:64
	ds_write_b32 v183, v147 offset:128
	ds_write_b32 v183, v145 offset:192
	ds_write_b32 v183, v143 offset:256
	ds_write_b32 v183, v141 offset:320
	ds_write_b32 v183, v139 offset:384
	ds_write_b32 v183, v135 offset:448
	v_writelane_b32 v248, s53, 41
	s_branch .Lepc_join

.LBB0_435:
	s_or_b64 exec, exec, s[50:51]
	v_and_b32_e32 v143, 64, v222
	v_xor_b32_e32 v142, 16, v222
	v_add_u32_e32 v148, 64, v143
	v_cmp_lt_i32_e32 vcc, v142, v148
	v_pk_add_f32 v[132:133], v[180:181], v[132:133]
	v_pk_add_f32 v[128:129], v[184:185], v[128:129]
	v_cndmask_b32_e32 v142, v222, v142, vcc
	v_lshlrev_b32_e32 v206, 2, v142
	v_mov_b32_e32 v142, v128
	v_mov_b32_e32 v143, v132
	v_mov_b32_e32 v132, v129
	v_pk_add_f32 v[128:129], v[142:143], v[132:133]
	v_mov_b32_e32 v133, v129
	s_nop 1
	v_permlane16_swap_b32_e32 v129, v133
	v_mov_b32_e32 v132, v128
	s_nop 1
	v_permlane16_swap_b32_e32 v128, v132
	v_xor_b32_e32 v142, 32, v222
	v_cmp_lt_i32_e32 vcc, v142, v148
	s_cmp_ge_i32 s62, s17
	s_cselect_b64 s[54:55], -1, 0
	v_cndmask_b32_e32 v142, v222, v142, vcc
	v_lshlrev_b32_e32 v180, 2, v142
	s_waitcnt lgkmcnt(0)
	v_pk_add_f32 v[128:129], v[128:129], v[132:133]
	v_mov_b32_e32 v133, v129
	s_nop 1
	v_permlane32_swap_b32_e32 v129, v133
	v_mov_b32_e32 v132, v128
	s_nop 1
	v_permlane32_swap_b32_e32 v128, v132
	s_cmp_lt_i32 s62, s17
	s_waitcnt lgkmcnt(0)
	v_pk_add_f32 v[128:129], v[128:129], v[132:133]
	s_nop 0
	v_pk_fma_f32 v[152:153], s[18:19], v[128:129], v[198:199] op_sel_hi:[1,1,0]
	v_pk_add_f32 v[132:133], v[186:187], v[134:135]
	v_mul_f32_e32 v128, 0x4b800000, v153
	v_cmp_gt_f32_e32 vcc, s39, v153
	v_mov_b32_e32 v134, v132
	v_cmp_gt_f32_e64 s[50:51], s39, v152
	v_cndmask_b32_e32 v128, v153, v128, vcc
	v_rsq_f32_e32 v142, v128
	v_pk_add_f32 v[128:129], v[182:183], v[138:139]
	v_pk_add_f32 v[138:139], v[192:193], v[146:147]
	v_mov_b32_e32 v135, v128
	v_mov_b32_e32 v128, v133
	v_pk_add_f32 v[132:133], v[134:135], v[128:129]
	v_mov_b32_e32 v135, v133
	s_nop 1
	v_permlane16_swap_b32_e32 v133, v135
	v_mov_b32_e32 v134, v132
	s_nop 1
	v_permlane16_swap_b32_e32 v132, v134
	v_mul_f32_e32 v128, 0x45800000, v142
	v_cndmask_b32_e32 v128, v142, v128, vcc
	v_pk_mul_f32 v[146:147], v[124:125], v[128:129] op_sel_hi:[1,0]
	v_pk_mul_f32 v[122:123], v[122:123], v[128:129] op_sel_hi:[1,0]
	s_waitcnt lgkmcnt(0)
	v_pk_add_f32 v[142:143], v[132:133], v[134:135]
	v_pk_add_f32 v[132:133], v[136:137], v[144:145]
	v_pk_add_f32 v[134:135], v[188:189], v[140:141]
	v_mov_b32_e32 v137, v132
	v_mov_b32_e32 v136, v134
	v_mov_b32_e32 v132, v135
	v_pk_add_f32 v[132:133], v[136:137], v[132:133]
	v_pk_add_f32 v[136:137], v[190:191], v[150:151]
	v_mov_b32_e32 v140, v138
	v_mov_b32_e32 v141, v136
	v_mov_b32_e32 v136, v139
	v_pk_add_f32 v[140:141], v[140:141], v[136:137]
	v_mov_b32_e32 v135, v133
	s_nop 1
	v_permlane16_swap_b32_e32 v133, v135
	v_mov_b32_e32 v134, v132
	s_nop 1
	v_permlane16_swap_b32_e32 v132, v134
	v_mov_b32_e32 v145, v141
	s_nop 1
	v_permlane16_swap_b32_e32 v141, v145
	v_mov_b32_e32 v144, v140
	s_nop 1
	v_permlane16_swap_b32_e32 v140, v144
	ds_bpermute_b32 v149, v180, v143
	ds_bpermute_b32 v148, v180, v142
	s_waitcnt lgkmcnt(0)
	v_pk_add_f32 v[136:137], v[132:133], v[134:135]
	ds_bpermute_b32 v139, v180, v137
	v_pk_add_f32 v[132:133], v[140:141], v[144:145]
	ds_bpermute_b32 v138, v180, v136
	ds_bpermute_b32 v135, v180, v133
	ds_bpermute_b32 v134, v180, v132
	v_pk_mul_f32 v[144:145], v[126:127], v[128:129] op_sel_hi:[1,0]
	v_pk_mul_f32 v[140:141], v[120:121], v[128:129] op_sel_hi:[1,0]
	s_cbranch_scc1 .LBB0_437
	v_and_b32_e32 v121, 0x7fffffff, v147
	v_and_b32_e32 v120, 0x7fffffff, v146
	v_pk_fma_f32 v[120:121], v[120:121], s[98:99], 1.0 op_sel_hi:[1,0,0]
	v_mov_b64_e32 v[124:125], s[10:11]
	v_rcp_f32_e32 v120, v120
	v_rcp_f32_e32 v121, v121
	v_pk_mul_f32 v[150:151], v[146:147], v[146:147]
	v_and_b32_e32 v183, 0x7fffffff, v145
	v_and_b32_e32 v182, 0x7fffffff, v144
	v_pk_fma_f32 v[126:127], v[120:121], s[38:39], v[124:125] op_sel_hi:[1,0,0]
	v_pk_mul_f32 v[150:151], v[150:151], s[16:17] op_sel_hi:[1,0]
	v_pk_fma_f32 v[182:183], v[182:183], s[98:99], 1.0 op_sel_hi:[1,0,0]
	v_pk_fma_f32 v[126:127], v[120:121], v[126:127], s[58:59] op_sel_hi:[1,1,0]
	v_exp_f32_e32 v150, v150
	v_exp_f32_e32 v151, v151
	v_rcp_f32_e32 v182, v182
	v_rcp_f32_e32 v183, v183
	v_pk_fma_f32 v[126:127], v[120:121], v[126:127], s[90:91] op_sel_hi:[1,1,0]
	v_pk_mul_f32 v[184:185], v[144:145], v[144:145]
	v_pk_fma_f32 v[126:127], v[120:121], v[126:127], s[0:1] op_sel_hi:[1,1,0]
	v_and_b32_e32 v187, 0x7fffffff, v141
	v_pk_mul_f32 v[120:121], v[120:121], v[126:127]
	v_and_b32_e32 v186, 0x7fffffff, v140
	v_pk_mul_f32 v[120:121], v[150:151], v[120:121]
	v_pk_fma_f32 v[150:151], v[182:183], s[38:39], v[124:125] op_sel_hi:[1,0,0]
	v_pk_mul_f32 v[184:185], v[184:185], s[16:17] op_sel_hi:[1,0]
	v_pk_fma_f32 v[186:187], v[186:187], s[98:99], 1.0 op_sel_hi:[1,0,0]
	v_pk_fma_f32 v[150:151], v[182:183], v[150:151], s[58:59] op_sel_hi:[1,1,0]
	v_exp_f32_e32 v184, v184
	v_exp_f32_e32 v185, v185
	v_rcp_f32_e32 v186, v186
	v_rcp_f32_e32 v187, v187
	v_pk_fma_f32 v[150:151], v[182:183], v[150:151], s[90:91] op_sel_hi:[1,1,0]
	v_pk_mul_f32 v[188:189], v[140:141], v[140:141]
	v_pk_fma_f32 v[150:151], v[182:183], v[150:151], s[0:1] op_sel_hi:[1,1,0]
	v_pk_mul_f32 v[188:189], v[188:189], s[16:17] op_sel_hi:[1,0]
	v_pk_mul_f32 v[150:151], v[182:183], v[150:151]
	v_and_b32_e32 v191, 0x7fffffff, v123
	v_pk_mul_f32 v[150:151], v[184:185], v[150:151]
	v_pk_fma_f32 v[184:185], v[186:187], s[38:39], v[124:125] op_sel_hi:[1,0,0]
	v_and_b32_e32 v190, 0x7fffffff, v122
	v_pk_fma_f32 v[184:185], v[186:187], v[184:185], s[58:59] op_sel_hi:[1,1,0]
	v_exp_f32_e32 v188, v188
	v_exp_f32_e32 v189, v189
	v_pk_fma_f32 v[190:191], v[190:191], s[98:99], 1.0 op_sel_hi:[1,0,0]
	v_pk_fma_f32 v[184:185], v[186:187], v[184:185], s[90:91] op_sel_hi:[1,1,0]
	v_rcp_f32_e32 v190, v190
	v_rcp_f32_e32 v191, v191
	v_pk_fma_f32 v[184:185], v[186:187], v[184:185], s[0:1] op_sel_hi:[1,1,0]
	v_pk_mul_f32 v[126:127], v[146:147], v[120:121]
	v_pk_mul_f32 v[184:185], v[186:187], v[184:185]
	v_pk_fma_f32 v[124:125], v[190:191], s[38:39], v[124:125] op_sel_hi:[1,0,0]
	v_pk_mul_f32 v[184:185], v[188:189], v[184:185]
	v_pk_mul_f32 v[188:189], v[122:123], v[122:123]
	v_pk_fma_f32 v[120:121], v[146:147], v[120:121], v[146:147] neg_lo:[1,0,0] neg_hi:[1,0,0]
	v_pk_mul_f32 v[188:189], v[188:189], s[16:17] op_sel_hi:[1,0]
	v_cmp_gt_f32_e32 vcc, 0, v146
	v_pk_fma_f32 v[124:125], v[190:191], v[124:125], s[58:59] op_sel_hi:[1,1,0]
	v_exp_f32_e32 v188, v188
	v_exp_f32_e32 v189, v189
	v_cndmask_b32_e32 v146, v120, v126, vcc
	v_cmp_gt_f32_e32 vcc, 0, v147
	v_pk_mul_f32 v[182:183], v[144:145], v[150:151]
	v_pk_fma_f32 v[124:125], v[190:191], v[124:125], s[90:91] op_sel_hi:[1,1,0]
	v_pk_fma_f32 v[150:151], v[144:145], v[150:151], v[144:145] neg_lo:[1,0,0] neg_hi:[1,0,0]
	v_cndmask_b32_e32 v147, v121, v127, vcc
	v_cmp_gt_f32_e32 vcc, 0, v144
	v_pk_fma_f32 v[124:125], v[190:191], v[124:125], s[0:1] op_sel_hi:[1,1,0]
	v_pk_mul_f32 v[186:187], v[140:141], v[184:185]
	v_cndmask_b32_e32 v144, v150, v182, vcc
	v_cmp_gt_f32_e32 vcc, 0, v145
	v_pk_mul_f32 v[124:125], v[190:191], v[124:125]
	v_pk_fma_f32 v[184:185], v[140:141], v[184:185], v[140:141] neg_lo:[1,0,0] neg_hi:[1,0,0]
	v_cndmask_b32_e32 v145, v151, v183, vcc
	v_cmp_gt_f32_e32 vcc, 0, v140
	v_pk_mul_f32 v[124:125], v[188:189], v[124:125]
	s_nop 0
	v_cndmask_b32_e32 v140, v184, v186, vcc
	v_cmp_gt_f32_e32 vcc, 0, v141
	v_pk_mul_f32 v[188:189], v[122:123], v[124:125]
	v_pk_fma_f32 v[124:125], v[122:123], v[124:125], v[122:123] neg_lo:[1,0,0] neg_hi:[1,0,0]
	v_cndmask_b32_e32 v141, v185, v187, vcc
	v_cmp_gt_f32_e32 vcc, 0, v122
	s_nop 1
	v_cndmask_b32_e32 v122, v124, v188, vcc
	v_cmp_gt_f32_e32 vcc, 0, v123
	s_nop 1
	v_cndmask_b32_e32 v123, v125, v189, vcc

.LBB0_439:
	s_lshl_b32 s92, s62, 3
	s_lshr_b64 s[56:57], s[20:21], s92
	s_and_b32 s60, s56, 3
	v_sub_u32_e64 v124, s60, 1 clamp
	v_lshlrev_b32_e32 v196, 20, v124
	v_lshlrev_b32_e32 v124, 3, v124
	s_mov_b32 s36, 0xa0300
	v_lshrrev_b32_e64 v124, v124, s36
	s_lshl_b32 s79, s62, 1
	v_and_b32_e32 v124, 11, v124
	v_sub_u32_e32 v124, s79, v124
	v_lshlrev_b32_e32 v124, 2, v124
	v_ashrrev_i32_e32 v125, 31, v124
	v_lshl_add_u64 v[120:121], s[4:5], 0, v[196:197]
	s_cmp_lg_u32 s60, 0
	v_lshlrev_b64 v[124:125], 2, v[124:125]
	s_cselect_b64 s[56:57], -1, 0
	v_lshl_add_u64 v[120:121], v[120:121], 0, v[124:125]
	s_lshl_b32 s36, s11, 2
	s_cmp_eq_u32 s60, 0
	v_lshl_add_u64 v[124:125], v[120:121], 0, s[36:37]
	s_cbranch_scc1 .LBB0_443
	v_mul_f32_e32 v120, v147, v147
	v_fmac_f32_e32 v120, v146, v146
	v_fmac_f32_e32 v120, v144, v144
	v_fmac_f32_e32 v120, v145, v145
	v_fmac_f32_e32 v120, v140, v140
	v_fmac_f32_e32 v120, v141, v141
	v_fmac_f32_e32 v120, v122, v122
	v_fmac_f32_e32 v120, v123, v123
	v_mov_b32_e32 v121, v120
	s_nop 1
	v_permlane16_swap_b32_e32 v120, v121
	s_waitcnt lgkmcnt(0)
	v_add_f32_e32 v120, v120, v121
	v_mov_b32_e32 v121, v120
	s_nop 1
	v_permlane32_swap_b32_e32 v120, v121
	s_and_saveexec_b64 s[60:61], s[44:45]
	s_cbranch_execz .LBB0_442
	s_waitcnt lgkmcnt(0)
	v_add_f32_e32 v126, v120, v121
	v_lshlrev_b64 v[120:121], 6, v[178:179]
	v_lshl_add_u64 v[120:121], v[124:125], 0, v[120:121]
	global_store_dword v[120:121], v126, off

.LBB0_448:
	v_mul_f32_e32 v112, v145, v145
	v_fmac_f32_e32 v112, v144, v144
	v_fmac_f32_e32 v112, v140, v140
	v_fmac_f32_e32 v112, v141, v141
	v_fmac_f32_e32 v112, v118, v118
	v_fmac_f32_e32 v112, v119, v119
	v_fmac_f32_e32 v112, v114, v114
	v_fmac_f32_e32 v112, v115, v115
	v_mov_b32_e32 v113, v112
	s_nop 1
	v_permlane16_swap_b32_e32 v112, v113
	s_waitcnt lgkmcnt(0)
	v_add_f32_e32 v112, v112, v113
	v_mov_b32_e32 v113, v112
	s_nop 1
	v_permlane32_swap_b32_e32 v112, v113
	s_and_saveexec_b64 s[56:57], s[44:45]
	s_cbranch_execz .LBB0_450
	s_waitcnt lgkmcnt(0)
	v_add_f32_e32 v116, v112, v113
	v_lshlrev_b64 v[112:113], 6, v[176:177]
	v_lshl_add_u64 v[112:113], v[124:125], 0, v[112:113]
	global_store_dword v[112:113], v116, off

.LBB0_456:
	v_mul_f32_e32 v110, v119, v119
	v_fmac_f32_e32 v110, v118, v118
	v_fmac_f32_e32 v110, v108, v108
	v_fmac_f32_e32 v110, v109, v109
	v_fmac_f32_e32 v110, v104, v104
	v_fmac_f32_e32 v110, v105, v105
	v_fmac_f32_e32 v110, v106, v106
	v_fmac_f32_e32 v110, v107, v107
	v_mov_b32_e32 v111, v110
	s_nop 1
	v_permlane16_swap_b32_e32 v110, v111
	s_waitcnt lgkmcnt(0)
	v_add_f32_e32 v110, v110, v111
	v_mov_b32_e32 v111, v110
	s_nop 1
	v_permlane32_swap_b32_e32 v110, v111
	s_and_saveexec_b64 s[60:61], s[44:45]
	s_cbranch_execz .LBB0_458
	s_waitcnt lgkmcnt(0)
	v_add_f32_e32 v113, v110, v111
	v_lshlrev_b64 v[110:111], 6, v[174:175]
	v_lshl_add_u64 v[110:111], v[124:125], 0, v[110:111]
	global_store_dword v[110:111], v113, off

.LBB0_464:
	v_mul_f32_e32 v96, v111, v111
	v_fmac_f32_e32 v96, v110, v110
	v_fmac_f32_e32 v96, v108, v108
	v_fmac_f32_e32 v96, v109, v109
	v_fmac_f32_e32 v96, v102, v102
	v_fmac_f32_e32 v96, v103, v103
	v_fmac_f32_e32 v96, v98, v98
	v_fmac_f32_e32 v96, v99, v99
	v_mov_b32_e32 v97, v96
	s_nop 1
	v_permlane16_swap_b32_e32 v96, v97
	s_waitcnt lgkmcnt(0)
	v_add_f32_e32 v96, v96, v97
	v_mov_b32_e32 v97, v96
	s_nop 1
	v_permlane32_swap_b32_e32 v96, v97
	s_and_saveexec_b64 s[56:57], s[44:45]
	s_cbranch_execz .LBB0_466
	s_waitcnt lgkmcnt(0)
	v_add_f32_e32 v100, v96, v97
	v_lshlrev_b64 v[96:97], 6, v[172:173]
	v_lshl_add_u64 v[96:97], v[124:125], 0, v[96:97]
	global_store_dword v[96:97], v100, off

.LBB0_472:
	v_mul_f32_e32 v94, v103, v103
	v_fmac_f32_e32 v94, v102, v102
	v_fmac_f32_e32 v94, v92, v92
	v_fmac_f32_e32 v94, v93, v93
	v_fmac_f32_e32 v94, v88, v88
	v_fmac_f32_e32 v94, v89, v89
	v_fmac_f32_e32 v94, v90, v90
	v_fmac_f32_e32 v94, v91, v91
	v_mov_b32_e32 v95, v94
	s_nop 1
	v_permlane16_swap_b32_e32 v94, v95
	s_waitcnt lgkmcnt(0)
	v_add_f32_e32 v94, v94, v95
	v_mov_b32_e32 v95, v94
	s_nop 1
	v_permlane32_swap_b32_e32 v94, v95
	s_and_saveexec_b64 s[60:61], s[44:45]
	s_cbranch_execz .LBB0_474
	s_waitcnt lgkmcnt(0)
	v_add_f32_e32 v97, v94, v95
	v_lshlrev_b64 v[94:95], 6, v[130:131]
	v_lshl_add_u64 v[94:95], v[124:125], 0, v[94:95]
	global_store_dword v[94:95], v97, off

.LBB0_480:
	v_mul_f32_e32 v82, v95, v95
	v_fmac_f32_e32 v82, v94, v94
	v_fmac_f32_e32 v82, v92, v92
	v_fmac_f32_e32 v82, v93, v93
	v_fmac_f32_e32 v82, v84, v84
	v_fmac_f32_e32 v82, v85, v85
	v_fmac_f32_e32 v82, v100, v100
	v_fmac_f32_e32 v82, v101, v101
	v_mov_b32_e32 v83, v82
	s_nop 1
	v_permlane16_swap_b32_e32 v82, v83
	s_waitcnt lgkmcnt(0)
	v_add_f32_e32 v82, v82, v83
	v_mov_b32_e32 v83, v82
	s_nop 1
	v_permlane32_swap_b32_e32 v82, v83
	s_and_saveexec_b64 s[56:57], s[44:45]
	s_cbranch_execz .LBB0_482
	s_waitcnt lgkmcnt(0)
	v_add_f32_e32 v86, v82, v83
	v_lshlrev_b64 v[82:83], 6, v[80:81]
	v_lshl_add_u64 v[82:83], v[124:125], 0, v[82:83]
	global_store_dword v[82:83], v86, off

.LBB0_488:
	v_mul_f32_e32 v74, v93, v93
	v_fmac_f32_e32 v74, v92, v92
	v_fmac_f32_e32 v74, v78, v78
	v_fmac_f32_e32 v74, v79, v79
	v_fmac_f32_e32 v74, v76, v76
	v_fmac_f32_e32 v74, v77, v77
	v_fmac_f32_e32 v74, v94, v94
	v_fmac_f32_e32 v74, v95, v95
	v_mov_b32_e32 v75, v74
	s_nop 1
	v_permlane16_swap_b32_e32 v74, v75
	s_waitcnt lgkmcnt(0)
	v_add_f32_e32 v74, v74, v75
	v_mov_b32_e32 v75, v74
	s_nop 1
	v_permlane32_swap_b32_e32 v74, v75
	s_and_saveexec_b64 s[60:61], s[44:45]
	s_cbranch_execz .LBB0_490
	s_waitcnt lgkmcnt(0)
	v_add_f32_e32 v83, v74, v75
	v_lshlrev_b64 v[74:75], 6, v[72:73]
	v_lshl_add_u64 v[74:75], v[124:125], 0, v[74:75]
	global_store_dword v[74:75], v83, off

.LBB0_496:
	v_mul_f32_e32 v75, v79, v79
	v_fmac_f32_e32 v75, v78, v78
	v_fmac_f32_e32 v75, v70, v70
	v_fmac_f32_e32 v75, v71, v71
	v_fmac_f32_e32 v75, v68, v68
	v_fmac_f32_e32 v75, v69, v69
	v_fmac_f32_e32 v75, v66, v66
	v_fmac_f32_e32 v75, v67, v67
	v_mov_b32_e32 v83, v75
	s_nop 1
	v_permlane16_swap_b32_e32 v75, v83
	s_waitcnt lgkmcnt(0)
	v_add_f32_e32 v75, v75, v83
	v_mov_b32_e32 v83, v75
	s_nop 1
	v_permlane32_swap_b32_e32 v75, v83
	s_and_saveexec_b64 s[52:53], s[44:45]
	s_cbranch_execz .LBB0_498
	v_lshlrev_b64 v[86:87], 6, v[64:65]
	s_waitcnt lgkmcnt(0)
	v_add_f32_e32 v75, v75, v83
	v_lshl_add_u64 v[86:87], v[124:125], 0, v[86:87]
	global_store_dword v[86:87], v75, off

.LBB0_503:
	s_or_b32 s54, s92, 4
	s_lshr_b64 s[54:55], s[20:21], s54
	s_and_b32 s54, s54, 3
	v_sub_u32_e64 v70, s54, 1 clamp
	v_lshlrev_b32_e32 v196, 20, v70
	v_lshlrev_b32_e32 v70, 3, v70
	s_mov_b32 s55, 0xa0300
	v_lshrrev_b32_e64 v70, v70, s55
	s_cmp_lg_u32 s54, 0
	v_and_b32_e32 v70, 11, v70
	s_cselect_b64 s[56:57], -1, 0
	s_or_b32 s55, s79, 1
	v_sub_u32_e32 v70, s55, v70
	v_lshlrev_b32_e32 v70, 2, v70
	v_ashrrev_i32_e32 v71, 31, v70
	v_lshl_add_u64 v[56:57], s[4:5], 0, v[196:197]
	v_lshlrev_b64 v[70:71], 2, v[70:71]
	v_lshl_add_u64 v[56:57], v[56:57], 0, v[70:71]
	s_cmp_eq_u32 s54, 0
	v_lshl_add_u64 v[56:57], v[56:57], 0, s[36:37]
	s_cbranch_scc1 .LBB0_507
	v_mul_f32_e32 v70, v69, v69
	v_fmac_f32_e32 v70, v68, v68
	v_fmac_f32_e32 v70, v62, v62
	v_fmac_f32_e32 v70, v63, v63
	v_fmac_f32_e32 v70, v60, v60
	v_fmac_f32_e32 v70, v61, v61
	v_fmac_f32_e32 v70, v58, v58
	v_fmac_f32_e32 v70, v59, v59
	v_mov_b32_e32 v71, v70
	s_nop 1
	v_permlane16_swap_b32_e32 v70, v71
	s_waitcnt lgkmcnt(0)
	v_add_f32_e32 v70, v70, v71
	v_mov_b32_e32 v71, v70
	s_nop 1
	v_permlane32_swap_b32_e32 v70, v71
	s_and_saveexec_b64 s[54:55], s[44:45]
	s_cbranch_execz .LBB0_506
	s_waitcnt lgkmcnt(0)
	v_add_f32_e32 v75, v70, v71
	v_lshlrev_b64 v[70:71], 6, v[178:179]
	v_lshl_add_u64 v[70:71], v[56:57], 0, v[70:71]
	global_store_dword v[70:71], v75, off

.LBB0_512:
	v_mul_f32_e32 v54, v59, v59
	v_fmac_f32_e32 v54, v58, v58
	v_fmac_f32_e32 v54, v52, v52
	v_fmac_f32_e32 v54, v53, v53
	v_fmac_f32_e32 v54, v48, v48
	v_fmac_f32_e32 v54, v49, v49
	v_fmac_f32_e32 v54, v50, v50
	v_fmac_f32_e32 v54, v51, v51
	v_mov_b32_e32 v55, v54
	s_nop 1
	v_permlane16_swap_b32_e32 v54, v55
	s_waitcnt lgkmcnt(0)
	v_add_f32_e32 v54, v54, v55
	v_mov_b32_e32 v55, v54
	s_nop 1
	v_permlane32_swap_b32_e32 v54, v55
	s_and_saveexec_b64 s[56:57], s[44:45]
	s_cbranch_execz .LBB0_514
	s_waitcnt lgkmcnt(0)
	v_add_f32_e32 v60, v54, v55
	v_lshlrev_b64 v[54:55], 6, v[176:177]
	v_lshl_add_u64 v[54:55], v[56:57], 0, v[54:55]
	global_store_dword v[54:55], v60, off

.LBB0_520:
	v_mul_f32_e32 v46, v49, v49
	v_fmac_f32_e32 v46, v48, v48
	v_fmac_f32_e32 v46, v44, v44
	v_fmac_f32_e32 v46, v45, v45
	v_fmac_f32_e32 v46, v40, v40
	v_fmac_f32_e32 v46, v41, v41
	v_fmac_f32_e32 v46, v42, v42
	v_fmac_f32_e32 v46, v43, v43
	v_mov_b32_e32 v47, v46
	s_nop 1
	v_permlane16_swap_b32_e32 v46, v47
	s_waitcnt lgkmcnt(0)
	v_add_f32_e32 v46, v46, v47
	v_mov_b32_e32 v47, v46
	s_nop 1
	v_permlane32_swap_b32_e32 v46, v47
	s_and_saveexec_b64 s[56:57], s[44:45]
	s_cbranch_execz .LBB0_522
	s_waitcnt lgkmcnt(0)
	v_add_f32_e32 v50, v46, v47
	v_lshlrev_b64 v[46:47], 6, v[174:175]
	v_lshl_add_u64 v[46:47], v[56:57], 0, v[46:47]
	global_store_dword v[46:47], v50, off

.LBB0_528:
	v_mul_f32_e32 v38, v41, v41
	v_fmac_f32_e32 v38, v40, v40
	v_fmac_f32_e32 v38, v36, v36
	v_fmac_f32_e32 v38, v37, v37
	v_fmac_f32_e32 v38, v32, v32
	v_fmac_f32_e32 v38, v33, v33
	v_fmac_f32_e32 v38, v34, v34
	v_fmac_f32_e32 v38, v35, v35
	v_mov_b32_e32 v39, v38
	s_nop 1
	v_permlane16_swap_b32_e32 v38, v39
	s_waitcnt lgkmcnt(0)
	v_add_f32_e32 v38, v38, v39
	v_mov_b32_e32 v39, v38
	s_nop 1
	v_permlane32_swap_b32_e32 v38, v39
	s_and_saveexec_b64 s[56:57], s[44:45]
	s_cbranch_execz .LBB0_530
	s_waitcnt lgkmcnt(0)
	v_add_f32_e32 v42, v38, v39
	v_lshlrev_b64 v[38:39], 6, v[172:173]
	v_lshl_add_u64 v[38:39], v[56:57], 0, v[38:39]
	global_store_dword v[38:39], v42, off

.LBB0_536:
	v_mul_f32_e32 v30, v33, v33
	v_fmac_f32_e32 v30, v32, v32
	v_fmac_f32_e32 v30, v28, v28
	v_fmac_f32_e32 v30, v29, v29
	v_fmac_f32_e32 v30, v24, v24
	v_fmac_f32_e32 v30, v25, v25
	v_fmac_f32_e32 v30, v26, v26
	v_fmac_f32_e32 v30, v27, v27
	v_mov_b32_e32 v31, v30
	s_nop 1
	v_permlane16_swap_b32_e32 v30, v31
	s_waitcnt lgkmcnt(0)
	v_add_f32_e32 v30, v30, v31
	v_mov_b32_e32 v31, v30
	s_nop 1
	v_permlane32_swap_b32_e32 v30, v31
	s_and_saveexec_b64 s[56:57], s[44:45]
	s_cbranch_execz .LBB0_538
	s_waitcnt lgkmcnt(0)
	v_add_f32_e32 v34, v30, v31
	v_lshlrev_b64 v[30:31], 6, v[130:131]
	v_lshl_add_u64 v[30:31], v[56:57], 0, v[30:31]
	global_store_dword v[30:31], v34, off

.LBB0_544:
	v_mul_f32_e32 v22, v25, v25
	v_fmac_f32_e32 v22, v24, v24
	v_fmac_f32_e32 v22, v20, v20
	v_fmac_f32_e32 v22, v21, v21
	v_fmac_f32_e32 v22, v16, v16
	v_fmac_f32_e32 v22, v17, v17
	v_fmac_f32_e32 v22, v18, v18
	v_fmac_f32_e32 v22, v19, v19
	v_mov_b32_e32 v23, v22
	s_nop 1
	v_permlane16_swap_b32_e32 v22, v23
	s_waitcnt lgkmcnt(0)
	v_add_f32_e32 v22, v22, v23
	v_mov_b32_e32 v23, v22
	s_nop 1
	v_permlane32_swap_b32_e32 v22, v23
	s_and_saveexec_b64 s[56:57], s[44:45]
	s_cbranch_execz .LBB0_546
	s_waitcnt lgkmcnt(0)
	v_add_f32_e32 v26, v22, v23
	v_lshlrev_b64 v[22:23], 6, v[80:81]
	v_lshl_add_u64 v[22:23], v[56:57], 0, v[22:23]
	global_store_dword v[22:23], v26, off

.LBB0_552:
	v_mul_f32_e32 v14, v17, v17
	v_fmac_f32_e32 v14, v16, v16
	v_fmac_f32_e32 v14, v12, v12
	v_fmac_f32_e32 v14, v13, v13
	v_fmac_f32_e32 v14, v8, v8
	v_fmac_f32_e32 v14, v9, v9
	v_fmac_f32_e32 v14, v10, v10
	v_fmac_f32_e32 v14, v11, v11
	v_mov_b32_e32 v15, v14
	s_nop 1
	v_permlane16_swap_b32_e32 v14, v15
	s_waitcnt lgkmcnt(0)
	v_add_f32_e32 v14, v14, v15
	v_mov_b32_e32 v15, v14
	s_nop 1
	v_permlane32_swap_b32_e32 v14, v15
	s_and_saveexec_b64 s[56:57], s[44:45]
	s_cbranch_execz .LBB0_554
	s_waitcnt lgkmcnt(0)
	v_add_f32_e32 v18, v14, v15
	v_lshlrev_b64 v[14:15], 6, v[72:73]
	v_lshl_add_u64 v[14:15], v[56:57], 0, v[14:15]
	global_store_dword v[14:15], v18, off

.LBB0_560:
	v_mul_f32_e32 v6, v9, v9
	v_fmac_f32_e32 v6, v8, v8
	v_fmac_f32_e32 v6, v4, v4
	v_fmac_f32_e32 v6, v5, v5
	v_fmac_f32_e32 v6, v0, v0
	v_fmac_f32_e32 v6, v1, v1
	v_fmac_f32_e32 v6, v2, v2
	v_fmac_f32_e32 v6, v3, v3
	v_mov_b32_e32 v7, v6
	s_nop 1
	v_permlane16_swap_b32_e32 v6, v7
	s_waitcnt lgkmcnt(0)
	v_add_f32_e32 v6, v6, v7
	v_mov_b32_e32 v7, v6
	s_nop 1
	v_permlane32_swap_b32_e32 v6, v7
	s_and_saveexec_b64 s[50:51], s[44:45]
	s_cbranch_execz .LBB0_562
	s_waitcnt lgkmcnt(0)
	v_add_f32_e32 v10, v6, v7
	v_lshlrev_b64 v[6:7], 6, v[64:65]
	v_lshl_add_u64 v[6:7], v[56:57], 0, v[6:7]
	global_store_dword v[6:7], v10, off
